# adds (on v135): row-sum exchange no longer invalidates L2 after its spin (exchanged data is read with sc1 loads; nothing else produced this phase is consumed)
# baseline (speedup 1.0000x reference)
;     __device__ __forceinline__ void exchange(const f32x4 (&acc)[2][2][4][2], const Unit& u, int e, int wr, int wc, int fr, int fq) const {
;     ...
;         if (wid == 0) { unsigned sp = 0;
;             while ((unsigned)__builtin_amdgcn_readfirstlane((int)__hip_atomic_load(c, __ATOMIC_RELAXED, __HIP_MEMORY_SCOPE_AGENT)) < 16u) { __builtin_amdgcn_s_sleep(2); if (++sp > (1u << 22)) break; }
;             __builtin_amdgcn_fence(__ATOMIC_ACQUIRE, "agent");
;             if (lid == 0) FL[0] = 1u; }
.LBB0_98:
	s_and_saveexec_b64 s[54:55], s[46:47]
	s_cbranch_execz .LBB0_100
	v_readlane_b32 s65, v254, 31
	s_nop 1
	v_mov_b32_e32 v144, s65
	ds_write_b32 v144, v252

;     __device__ __forceinline__ void exchange(const f32x4 (&acc)[2][2][4][2], const Unit& u, int e, int wr, int wc, int fr, int fq) const {
;     ...
;         if (wid == 0) { unsigned sp = 0;
;             while ((unsigned)__builtin_amdgcn_readfirstlane((int)__hip_atomic_load(c, __ATOMIC_RELAXED, __HIP_MEMORY_SCOPE_AGENT)) < 16u) { __builtin_amdgcn_s_sleep(2); if (++sp > (1u << 22)) break; }
;             __builtin_amdgcn_fence(__ATOMIC_ACQUIRE, "agent");
;             if (lid == 0) FL[0] = 1u; }
.LBB0_134:
	s_and_saveexec_b64 s[12:13], s[46:47]
	s_cbranch_execz .LBB0_136
	v_readlane_b32 s50, v254, 31
	s_nop 1
	v_mov_b32_e32 v158, s50
	ds_write_b32 v158, v252

;     __device__ __forceinline__ void exchange(const f32x4 (&acc)[2][2][4][2], const Unit& u, int e, int wr, int wc, int fr, int fq) const {
;     ...
;         if (wid == 0) { unsigned sp = 0;
;             while ((unsigned)__builtin_amdgcn_readfirstlane((int)__hip_atomic_load(c, __ATOMIC_RELAXED, __HIP_MEMORY_SCOPE_AGENT)) < 16u) { __builtin_amdgcn_s_sleep(2); if (++sp > (1u << 22)) break; }
;             __builtin_amdgcn_fence(__ATOMIC_ACQUIRE, "agent");
;             if (lid == 0) FL[0] = 1u; }
.LBB0_230:
	s_and_saveexec_b64 s[54:55], s[46:47]
	s_cbranch_execz .LBB0_232
	v_readlane_b32 s68, v254, 31
	s_nop 1
	v_mov_b32_e32 v144, s68
	ds_write_b32 v144, v252

;     __device__ __forceinline__ void exchange(const f32x4 (&acc)[2][2][4][2], const Unit& u, int e, int wr, int wc, int fr, int fq) const {
;     ...
;         if (wid == 0) { unsigned sp = 0;
;             while ((unsigned)__builtin_amdgcn_readfirstlane((int)__hip_atomic_load(c, __ATOMIC_RELAXED, __HIP_MEMORY_SCOPE_AGENT)) < 16u) { __builtin_amdgcn_s_sleep(2); if (++sp > (1u << 22)) break; }
;             __builtin_amdgcn_fence(__ATOMIC_ACQUIRE, "agent");
;             if (lid == 0) FL[0] = 1u; }
.LBB0_266:
	s_and_saveexec_b64 s[12:13], s[46:47]
	s_cbranch_execz .LBB0_268
	v_readlane_b32 s50, v254, 31
	s_nop 1
	v_mov_b32_e32 v160, s50
	ds_write_b32 v160, v252
